# attention: LDS-DMA gather into XOR-swizzled unpadded image (no ds_write staging)
# baseline (speedup 1.0000x reference)
.LBB0_126:
	s_cmp_gt_i32 s76, -1
	s_cbranch_scc0 .LBB0_138
	s_mul_i32 s0, s22, 0x4200
	s_add_i32 s25, s0, 0
	s_mul_i32 s98, s22, 0x4200
	v_and_b32_e32 v174, 31, v165
	v_bfe_u32 v175, v165, 5, 1
	v_lshlrev_b32_e32 v174, 4, v174
	v_lshlrev_b32_e32 v175, 5, v175
	v_xor_b32_e32 v150, v174, v175
	v_xor_b32_e32 v151, 0x40, v150
	v_xor_b32_e32 v152, 0x80, v150
	v_xor_b32_e32 v153, 0xc0, v150
	v_and_b32_e32 v174, 15, v165
	v_lshl_add_u32 v154, v174, 9, s98
	v_bfe_u32 v175, v165, 4, 1
	v_lshl_or_b32 v154, v175, 4, v154
	v_bfe_u32 v175, v165, 5, 1
	v_xor_b32_e32 v175, v175, v174
	v_and_b32_e32 v175, 1, v175
	v_lshl_or_b32 v154, v175, 5, v154
	v_bfe_u32 v175, v165, 1, 2
	v_lshl_or_b32 v154, v175, 6, v154
	v_xor_b32_e32 v155, 0x40, v154
	v_xor_b32_e32 v156, 0x80, v154
	v_xor_b32_e32 v157, 0xc0, v154
	v_bfe_u32 v174, v165, 4, 2
	v_bfe_u32 v175, v165, 2, 2
	v_lshl_or_b32 v174, v174, 2, v175
	v_lshl_add_u32 v158, v174, 9, s98
	v_and_b32_e32 v174, 7, v174
	v_lshl_or_b32 v158, v174, 5, v158
	v_and_b32_e32 v175, 3, v165
	v_lshl_or_b32 v158, v175, 3, v158
	v_xor_b32_e32 v159, 0x20, v158
	v_xor_b32_e32 v160, 0x40, v158
	v_xor_b32_e32 v161, 0x60, v158
	v_xor_b32_e32 v162, 0x80, v158
	v_xor_b32_e32 v163, 0xa0, v158
	v_xor_b32_e32 v172, 0xc0, v158
	v_xor_b32_e32 v173, 0xe0, v158
	s_add_u32 s0, s78, 0x2b000000
	s_addc_u32 s1, s79, 0
	s_lshl_b64 s[2:3], s[76:77], 10
	v_and_b32_e32 v1, 63, v2
	s_add_u32 s2, s0, s2
	s_addc_u32 s3, s1, s3
	v_lshlrev_b32_e32 v4, 2, v1
	global_load_dword v124, v4, s[2:3]
	global_load_dword v125, v4, s[2:3] offset:256
	global_load_dword v126, v4, s[2:3] offset:512
	global_load_dword v127, v4, s[2:3] offset:768
	v_mov_b32_e32 v5, v32
	v_lshl_add_u64 v[34:35], s[0:1], 0, v[4:5]
	v_lshlrev_b32_e32 v4, 9, v0
	v_lshl_add_u64 v[6:7], s[16:17], 0, v[4:5]
	v_and_b32_e32 v10, 48, v2
	v_mov_b32_e32 v11, v32
	v_lshlrev_b32_e32 v3, 4, v2
	v_bfe_u32 v1, v2, 4, 2
	v_lshl_add_u64 v[100:101], v[6:7], 0, v[10:11]
	v_and_b32_e32 v6, 0x1f0, v3
	v_mov_b32_e32 v7, v32
	v_lshl_add_u64 v[12:13], s[78:79], 0, v[6:7]
	s_mov_b64 s[0:1], 0x2a300000
	v_lshlrev_b32_e32 v33, 2, v1
	v_lshrrev_b32_e32 v3, 2, v0
	v_lshlrev_b32_e32 v8, 3, v1
	v_lshl_add_u64 v[102:103], v[12:13], 0, s[0:1]
	v_bfe_u32 v7, v2, 5, 1
	v_add_u32_e32 v1, s25, v10
	v_or_b32_e32 v3, v33, v3
	v_mov_b32_e32 v10, s25
	s_movk_i32 s0, 0x210
	v_lshlrev_b32_e32 v2, 3, v2
	v_mov_b32_e32 v9, v32
	v_mad_u32_u24 v10, v3, s0, v10
	v_and_b32_e32 v11, 24, v2
	v_lshl_add_u64 v[2:3], s[78:79], 0, v[4:5]
	v_lshl_add_u64 v[2:3], v[2:3], 0, v[8:9]
	s_mov_b64 s[0:1], 0x2c000000
	v_lshl_add_u64 v[104:105], v[2:3], 0, s[0:1]
	v_cmp_lt_i32_e32 vcc, v186, v181
	s_lshl_b32 s0, s10, 11
	s_and_b32 s0, s0, 0x3000
	v_cndmask_b32_e32 v4, v179, v186, vcc
	v_cmp_lt_i32_e32 vcc, v187, v181
	v_add_u32_e32 v6, s25, v6
	v_mul_u32_u24_e32 v2, 0x210, v7
	v_mul_u32_u24_e32 v3, 0x210, v0
	v_lshlrev_b32_e32 v113, 2, v4
	v_cndmask_b32_e32 v4, v179, v187, vcc
	s_add_i32 s24, s24, s0
	v_readlane_b32 s0, v252, 29
	s_mov_b32 s2, 0
	v_or_b32_e32 v110, 1, v180
	v_or_b32_e32 v111, 2, v180
	v_or_b32_e32 v112, 3, v180
	v_lshlrev_b32_e32 v114, 2, v4
	v_or_b32_e32 v115, v180, v7
	v_lshl_add_u32 v116, v0, 2, s0
	v_add_u32_e32 v117, v6, v2
	v_add_u32_e32 v118, v1, v3
	v_add_u32_e32 v119, v10, v11
	s_waitcnt vmcnt(0)

.LBB0_135:
	s_and_b32 s0, s76, 0x7ffff000
	s_mov_b32 s1, s77
	s_lshl_b64 s[0:1], s[0:1], 9
	s_add_u32 s100, s78, s0
	s_addc_u32 s101, s79, s1
	s_add_u32 s100, s100, 0x2a300000
	s_addc_u32 s101, s101, 0
	v_mov_b32_e32 v72, 0
	s_and_b32 s29, s76, 0xfff
	v_mad_u64_u32 v[106:107], s[2:3], s76, v188, v[100:101]
	v_lshl_add_u64 v[108:109], v[102:103], 0, s[0:1]
	v_mov_b32_e32 v128, 0xff800000
	global_load_dwordx4 v[196:199], v[106:107], off
	global_load_dwordx4 v[200:203], v[106:107], off offset:64
	global_load_dwordx4 v[204:207], v[106:107], off offset:128
	global_load_dwordx4 v[208:211], v[106:107], off offset:192
	global_load_dwordx4 v[212:215], v[106:107], off offset:256
	global_load_dwordx4 v[216:219], v[106:107], off offset:320
	global_load_dwordx4 v[220:223], v[106:107], off offset:384
	global_load_dwordx4 v[224:227], v[106:107], off offset:448
	s_mov_b32 s30, 0
	v_mov_b32_e32 v68, 0
	v_mov_b32_e32 v69, v72
	v_mov_b32_e32 v70, v72
	v_mov_b32_e32 v71, v72
	v_mov_b32_e32 v24, 0
	v_mov_b32_e32 v25, v72
	v_mov_b32_e32 v26, v72
	v_mov_b32_e32 v27, v72
	v_mov_b32_e32 v64, 0
	v_mov_b32_e32 v65, v72
	v_mov_b32_e32 v66, v72
	v_mov_b32_e32 v67, v72
	v_mov_b32_e32 v60, 0
	v_mov_b32_e32 v61, v72
	v_mov_b32_e32 v62, v72
	v_mov_b32_e32 v63, v72
	v_mov_b32_e32 v56, 0
	v_mov_b32_e32 v57, v72
	v_mov_b32_e32 v58, v72
	v_mov_b32_e32 v59, v72
	v_mov_b32_e32 v52, 0
	v_mov_b32_e32 v53, v72
	v_mov_b32_e32 v54, v72
	v_mov_b32_e32 v55, v72
	v_mov_b32_e32 v48, 0
	v_mov_b32_e32 v49, v72
	v_mov_b32_e32 v50, v72
	v_mov_b32_e32 v51, v72
	v_mov_b32_e32 v44, 0
	v_mov_b32_e32 v45, v72
	v_mov_b32_e32 v46, v72
	v_mov_b32_e32 v47, v72
	v_mov_b32_e32 v40, 0
	v_mov_b32_e32 v41, v72
	v_mov_b32_e32 v42, v72
	v_mov_b32_e32 v43, v72
	v_mov_b32_e32 v28, 0
	v_mov_b32_e32 v29, v72
	v_mov_b32_e32 v30, v72
	v_mov_b32_e32 v31, v72
	v_mov_b32_e32 v20, 0
	v_mov_b32_e32 v21, v72
	v_mov_b32_e32 v22, v72
	v_mov_b32_e32 v23, v72
	v_mov_b32_e32 v16, 0
	v_mov_b32_e32 v17, v72
	v_mov_b32_e32 v18, v72
	v_mov_b32_e32 v19, v72
	v_mov_b32_e32 v12, 0
	v_mov_b32_e32 v13, v72
	v_mov_b32_e32 v14, v72
	v_mov_b32_e32 v15, v72
	v_mov_b32_e32 v8, 0
	v_mov_b32_e32 v9, v72
	v_mov_b32_e32 v10, v72
	v_mov_b32_e32 v11, v72
	v_mov_b32_e32 v4, 0
	v_mov_b32_e32 v5, v72
	v_mov_b32_e32 v6, v72
	v_mov_b32_e32 v7, v72
	v_mov_b32_e32 v0, 0
	v_mov_b32_e32 v1, v72
	v_mov_b32_e32 v2, v72
	v_mov_b32_e32 v3, v72
.LBB0_136:
	s_lshr_b32 s2, s30, 1
	s_cmp_lt_u32 s30, 2
	s_cselect_b64 vcc, -1, 0
	s_cmp_eq_u32 s2, 1
	s_cselect_b64 s[0:1], -1, 0
	s_cmp_eq_u32 s2, 2
	s_cselect_b64 s[2:3], -1, 0
	v_mov_b32_e32 v129, v72
	v_cndmask_b32_e64 v72, v127, v126, s[2:3]
	v_cndmask_b32_e64 v72, v72, v125, s[0:1]
	s_and_b32 s0, s28, 32
	v_cndmask_b32_e32 v130, v72, v124, vcc
	v_or_b32_e32 v72, s0, v115
	v_lshlrev_b32_e32 v131, 2, v72
	ds_bpermute_b32 v72, v131, v130
	ds_bpermute_b32 v73, v131, v130 offset:8
	ds_bpermute_b32 v74, v131, v130 offset:16
	ds_bpermute_b32 v75, v131, v130 offset:24
	ds_bpermute_b32 v76, v131, v130 offset:32
	ds_bpermute_b32 v77, v131, v130 offset:40
	ds_bpermute_b32 v78, v131, v130 offset:48
	ds_bpermute_b32 v79, v131, v130 offset:56
	s_mov_b32 m0, s98
	s_waitcnt lgkmcnt(7)
	v_max_i32_e32 v72, 0, v72
	v_lshl_or_b32 v72, v72, 9, v150
	global_load_lds_dwordx4 v72, s[100:101]
	s_add_u32 m0, m0, 0x400
	s_waitcnt lgkmcnt(6)
	v_max_i32_e32 v73, 0, v73
	v_lshl_or_b32 v73, v73, 9, v151
	global_load_lds_dwordx4 v73, s[100:101]
	s_add_u32 m0, m0, 0x400
	s_waitcnt lgkmcnt(5)
	v_max_i32_e32 v74, 0, v74
	v_lshl_or_b32 v74, v74, 9, v152
	global_load_lds_dwordx4 v74, s[100:101]
	s_add_u32 m0, m0, 0x400
	s_waitcnt lgkmcnt(4)
	v_max_i32_e32 v75, 0, v75
	v_lshl_or_b32 v75, v75, 9, v153
	global_load_lds_dwordx4 v75, s[100:101]
	s_add_u32 m0, m0, 0x400
	s_waitcnt lgkmcnt(3)
	v_max_i32_e32 v76, 0, v76
	v_lshl_or_b32 v76, v76, 9, v150
	global_load_lds_dwordx4 v76, s[100:101]
	s_add_u32 m0, m0, 0x400
	s_waitcnt lgkmcnt(2)
	v_max_i32_e32 v77, 0, v77
	v_lshl_or_b32 v77, v77, 9, v151
	global_load_lds_dwordx4 v77, s[100:101]
	s_add_u32 m0, m0, 0x400
	s_waitcnt lgkmcnt(1)
	v_max_i32_e32 v78, 0, v78
	v_lshl_or_b32 v78, v78, 9, v152
	global_load_lds_dwordx4 v78, s[100:101]
	s_add_u32 m0, m0, 0x400
	s_waitcnt lgkmcnt(0)
	v_max_i32_e32 v79, 0, v79
	v_lshl_or_b32 v79, v79, 9, v153
	global_load_lds_dwordx4 v79, s[100:101]
	s_add_u32 m0, m0, 0x400
	ds_bpermute_b32 v80, v131, v130 offset:64
	ds_bpermute_b32 v81, v131, v130 offset:72
	ds_bpermute_b32 v82, v131, v130 offset:80
	ds_bpermute_b32 v83, v131, v130 offset:88
	ds_bpermute_b32 v84, v131, v130 offset:96
	ds_bpermute_b32 v85, v131, v130 offset:104
	ds_bpermute_b32 v86, v131, v130 offset:112
	ds_bpermute_b32 v87, v131, v130 offset:120
	s_waitcnt lgkmcnt(7)
	v_max_i32_e32 v80, 0, v80
	v_lshl_or_b32 v80, v80, 9, v150
	global_load_lds_dwordx4 v80, s[100:101]
	s_add_u32 m0, m0, 0x400
	s_waitcnt lgkmcnt(6)
	v_max_i32_e32 v81, 0, v81
	v_lshl_or_b32 v81, v81, 9, v151
	global_load_lds_dwordx4 v81, s[100:101]
	s_add_u32 m0, m0, 0x400
	s_waitcnt lgkmcnt(5)
	v_max_i32_e32 v82, 0, v82
	v_lshl_or_b32 v82, v82, 9, v152
	global_load_lds_dwordx4 v82, s[100:101]
	s_add_u32 m0, m0, 0x400
	s_waitcnt lgkmcnt(4)
	v_max_i32_e32 v83, 0, v83
	v_lshl_or_b32 v83, v83, 9, v153
	global_load_lds_dwordx4 v83, s[100:101]
	s_add_u32 m0, m0, 0x400
	s_waitcnt lgkmcnt(3)
	v_max_i32_e32 v84, 0, v84
	v_lshl_or_b32 v84, v84, 9, v150
	global_load_lds_dwordx4 v84, s[100:101]
	s_add_u32 m0, m0, 0x400
	s_waitcnt lgkmcnt(2)
	v_max_i32_e32 v85, 0, v85
	v_lshl_or_b32 v85, v85, 9, v151
	global_load_lds_dwordx4 v85, s[100:101]
	s_add_u32 m0, m0, 0x400
	s_waitcnt lgkmcnt(1)
	v_max_i32_e32 v86, 0, v86
	v_lshl_or_b32 v86, v86, 9, v152
	global_load_lds_dwordx4 v86, s[100:101]
	s_add_u32 m0, m0, 0x400
	s_waitcnt lgkmcnt(0)
	v_max_i32_e32 v87, 0, v87
	v_lshl_or_b32 v87, v87, 9, v153
	global_load_lds_dwordx4 v87, s[100:101]
	s_add_u32 m0, m0, 0x400
	s_add_i32 s30, s30, 1
	s_add_i32 s28, s28, 32
	s_cmp_eq_u32 s30, 8
	v_or_b32_e32 v72, s0, v33
	v_or_b32_e32 v73, v72, v180
	v_lshlrev_b32_e32 v73, 2, v73
	ds_bpermute_b32 v138, v73, v130
	v_or_b32_e32 v73, v72, v110
	v_lshlrev_b32_e32 v73, 2, v73
	ds_bpermute_b32 v139, v73, v130
	v_or_b32_e32 v73, v72, v111
	v_lshlrev_b32_e32 v73, 2, v73
	ds_bpermute_b32 v140, v73, v130
	v_or_b32_e32 v73, v72, v112
	v_lshlrev_b32_e32 v73, 2, v73
	v_or_b32_e32 v72, 16, v72
	ds_bpermute_b32 v141, v73, v130
	v_or_b32_e32 v73, v72, v180
	v_lshlrev_b32_e32 v73, 2, v73
	ds_bpermute_b32 v142, v73, v130
	v_or_b32_e32 v73, v72, v110
	v_lshlrev_b32_e32 v73, 2, v73
	ds_bpermute_b32 v143, v73, v130
	v_or_b32_e32 v73, v72, v111
	v_or_b32_e32 v72, v72, v112
	v_lshlrev_b32_e32 v73, 2, v73
	v_lshlrev_b32_e32 v72, 2, v72
	s_mov_b64 s[0:1], 0
	ds_bpermute_b32 v148, v73, v130
	ds_bpermute_b32 v149, v72, v130
	s_waitcnt lgkmcnt(7)
	v_cmp_lt_i32_e32 vcc, -1, v138
	s_waitcnt lgkmcnt(0)
	s_waitcnt vmcnt(0)
	ds_read_b128 v[228:231], v154
	ds_read_b128 v[232:235], v155
	ds_read_b128 v[236:239], v156
	ds_read_b128 v[240:243], v157
	s_waitcnt lgkmcnt(3)
	v_mfma_f32_16x16x32_bf16 v[134:137], v[228:231], v[196:199], 0
	ds_read_b128 v[228:231], v154 offset:256
	s_waitcnt lgkmcnt(3)
	v_mfma_f32_16x16x32_bf16 v[134:137], v[232:235], v[200:203], v[134:137]
	ds_read_b128 v[232:235], v155 offset:256
	s_waitcnt lgkmcnt(3)
	v_mfma_f32_16x16x32_bf16 v[134:137], v[236:239], v[204:207], v[134:137]
	ds_read_b128 v[236:239], v156 offset:256
	s_waitcnt lgkmcnt(3)
	v_mfma_f32_16x16x32_bf16 v[134:137], v[240:243], v[208:211], v[134:137]
	ds_read_b128 v[240:243], v157 offset:256
	s_waitcnt lgkmcnt(3)
	v_mfma_f32_16x16x32_bf16 v[134:137], v[228:231], v[212:215], v[134:137]
	ds_read_b128 v[228:231], v154 offset:8192
	s_waitcnt lgkmcnt(3)
	v_mfma_f32_16x16x32_bf16 v[134:137], v[232:235], v[216:219], v[134:137]
	ds_read_b128 v[232:235], v155 offset:8192
	s_waitcnt lgkmcnt(3)
	v_mfma_f32_16x16x32_bf16 v[134:137], v[236:239], v[220:223], v[134:137]
	ds_read_b128 v[236:239], v156 offset:8192
	s_waitcnt lgkmcnt(3)
	v_mfma_f32_16x16x32_bf16 v[134:137], v[240:243], v[224:227], v[134:137]
	ds_read_b128 v[240:243], v157 offset:8192
	s_waitcnt lgkmcnt(3)
	v_mfma_f32_16x16x32_bf16 v[72:75], v[228:231], v[196:199], 0
	ds_read_b128 v[228:231], v154 offset:8448
	s_waitcnt lgkmcnt(3)
	v_mfma_f32_16x16x32_bf16 v[72:75], v[232:235], v[200:203], v[72:75]
	ds_read_b128 v[232:235], v155 offset:8448
	s_waitcnt lgkmcnt(3)
	v_mfma_f32_16x16x32_bf16 v[72:75], v[236:239], v[204:207], v[72:75]
	ds_read_b128 v[236:239], v156 offset:8448
	s_waitcnt lgkmcnt(3)
	v_mfma_f32_16x16x32_bf16 v[72:75], v[240:243], v[208:211], v[72:75]
	ds_read_b128 v[240:243], v157 offset:8448
	v_subrev_u32_e32 v80, s29, v142
	v_med3_i32 v80, v80, s4, v189
	v_lshl_add_u32 v80, v80, 6, v116
	ds_read_b32 v80, v80 offset:8192
	s_waitcnt lgkmcnt(4)
	v_mfma_f32_16x16x32_bf16 v[72:75], v[228:231], v[212:215], v[72:75]
	s_waitcnt lgkmcnt(3)
	v_mfma_f32_16x16x32_bf16 v[72:75], v[232:235], v[216:219], v[72:75]
	s_waitcnt lgkmcnt(2)
	v_mfma_f32_16x16x32_bf16 v[72:75], v[236:239], v[220:223], v[72:75]
	s_waitcnt lgkmcnt(1)
	v_mfma_f32_16x16x32_bf16 v[72:75], v[240:243], v[224:227], v[72:75]
	v_subrev_u32_e32 v76, s29, v138
	v_med3_i32 v76, v76, s4, v189
	v_subrev_u32_e32 v77, s29, v139
	v_lshl_add_u32 v76, v76, 6, v116
	v_med3_i32 v77, v77, s4, v189
	v_subrev_u32_e32 v78, s29, v140
	ds_read_b32 v76, v76 offset:8192
	v_lshl_add_u32 v77, v77, 6, v116
	v_med3_i32 v78, v78, s4, v189
	v_subrev_u32_e32 v79, s29, v141
	ds_read_b32 v77, v77 offset:8192
	v_lshl_add_u32 v78, v78, 6, v116
	v_med3_i32 v79, v79, s4, v189
	ds_read_b32 v78, v78 offset:8192
	v_lshl_add_u32 v79, v79, 6, v116
	ds_read_b32 v79, v79 offset:8192
	s_waitcnt lgkmcnt(3)
	v_fmac_f32_e32 v76, 0x3d800000, v134
	v_cndmask_b32_e32 v76, v190, v76, vcc
	s_waitcnt lgkmcnt(2)
	v_fmac_f32_e32 v77, 0x3d800000, v135
	v_cmp_lt_i32_e32 vcc, -1, v139
	s_waitcnt lgkmcnt(1)
	v_fmac_f32_e32 v78, 0x3d800000, v136
	s_waitcnt lgkmcnt(0)
	v_fmac_f32_e32 v79, 0x3d800000, v137
	v_cndmask_b32_e32 v77, v190, v77, vcc
	v_cmp_lt_i32_e32 vcc, -1, v140
	v_fmac_f32_e32 v80, 0x3d800000, v72
	s_nop 0
	v_cndmask_b32_e32 v78, v190, v78, vcc
	v_cmp_lt_i32_e32 vcc, -1, v141
	s_nop 1
	v_cndmask_b32_e32 v79, v190, v79, vcc
	v_cmp_lt_i32_e32 vcc, -1, v142
	v_max_f32_e32 v81, v78, v79
	s_nop 0
	v_cndmask_b32_e32 v72, v190, v80, vcc
	v_subrev_u32_e32 v80, s29, v143
	v_med3_i32 v80, v80, s4, v189
	v_lshl_add_u32 v80, v80, 6, v116
	ds_read_b32 v80, v80 offset:8192
	v_cmp_lt_i32_e32 vcc, -1, v143
	s_waitcnt lgkmcnt(0)
	v_fmac_f32_e32 v80, 0x3d800000, v73
	v_subrev_u32_e32 v73, s29, v148
	v_med3_i32 v73, v73, s4, v189
	v_lshl_add_u32 v73, v73, 6, v116
	ds_read_b32 v73, v73 offset:8192
	v_cndmask_b32_e32 v80, v190, v80, vcc
	v_cmp_lt_i32_e32 vcc, -1, v148
	s_waitcnt lgkmcnt(0)
	v_fmac_f32_e32 v73, 0x3d800000, v74
	v_cndmask_b32_e32 v74, v190, v73, vcc
	v_subrev_u32_e32 v73, s29, v149
	v_med3_i32 v73, v73, s4, v189
	v_lshl_add_u32 v73, v73, 6, v116
	ds_read_b32 v73, v73 offset:8192
	v_cmp_lt_i32_e32 vcc, -1, v149
	s_waitcnt lgkmcnt(0)
	v_fmac_f32_e32 v73, 0x3d800000, v75
	v_cndmask_b32_e32 v75, v190, v73, vcc
	v_max_f32_e32 v82, v74, v75
	v_max_f32_e32 v73, v76, v77
	v_max3_f32 v82, v72, v80, v82
	v_max3_f32 v73, v73, v81, v82
	ds_bpermute_b32 v81, v113, v73
	s_waitcnt lgkmcnt(0)
	v_max_f32_e32 v81, v81, v81
	v_max_f32_e32 v73, v73, v81
	ds_bpermute_b32 v81, v114, v73
	s_waitcnt lgkmcnt(0)
	v_max3_f32 v73, v128, v73, v81
	v_sub_f32_e32 v72, v72, v73
	v_mul_f32_e32 v72, 0x3fb8aa3b, v72
	v_sub_f32_e32 v76, v76, v73
	v_exp_f32_e32 v82, v72
	v_sub_f32_e32 v72, v80, v73
	v_mul_f32_e32 v76, 0x3fb8aa3b, v76
	v_sub_f32_e32 v77, v77, v73
	v_mul_f32_e32 v72, 0x3fb8aa3b, v72
	v_exp_f32_e32 v76, v76
	v_mul_f32_e32 v77, 0x3fb8aa3b, v77
	v_sub_f32_e32 v78, v78, v73
	v_exp_f32_e32 v80, v72
	v_sub_f32_e32 v72, v74, v73
	v_exp_f32_e32 v77, v77
	v_mul_f32_e32 v78, 0x3fb8aa3b, v78
	v_sub_f32_e32 v79, v79, v73
	v_mul_f32_e32 v72, 0x3fb8aa3b, v72
	v_exp_f32_e32 v78, v78
	v_mul_f32_e32 v79, 0x3fb8aa3b, v79
	v_exp_f32_e32 v83, v72
	v_sub_f32_e32 v72, v75, v73
	v_exp_f32_e32 v79, v79
	v_mul_f32_e32 v72, 0x3fb8aa3b, v72
	v_exp_f32_e32 v84, v72
	v_add_f32_e32 v72, 0, v76
	v_add_f32_e32 v72, v77, v72
	v_add_f32_e32 v72, v78, v72
	v_sub_f32_e32 v81, v128, v73
	v_add_f32_e32 v72, v79, v72
	v_mul_f32_e32 v81, 0x3fb8aa3b, v81
	v_add_f32_e32 v72, v82, v72
	v_exp_f32_e32 v86, v81
	v_add_f32_e32 v72, v80, v72
	v_add_f32_e32 v72, v83, v72
	v_cvt_pk_bf16_f32 v74, v76, v77
	v_cvt_pk_bf16_f32 v75, v78, v79
	v_cvt_pk_bf16_f32 v76, v82, v80
	v_cvt_pk_bf16_f32 v77, v83, v84
	ds_read_b64_tr_b16 v[80:81], v158 offset:8192
	ds_read_b64_tr_b16 v[78:79], v158
	ds_read_b64_tr_b16 v[82:83], v159
	v_pk_mul_f32 v[70:71], v[70:71], v[86:87] op_sel_hi:[1,0]
	v_pk_mul_f32 v[68:69], v[68:69], v[86:87] op_sel_hi:[1,0]
	v_add_f32_e32 v72, v84, v72
	ds_read_b64_tr_b16 v[84:85], v159 offset:8192
	s_waitcnt lgkmcnt(2)
	v_mfma_f32_16x16x32_bf16 v[68:71], v[78:81], v[74:77], v[68:71]
	ds_read_b64_tr_b16 v[78:79], v160
	ds_read_b64_tr_b16 v[80:81], v160 offset:8192
	v_pk_mul_f32 v[66:67], v[66:67], v[86:87] op_sel_hi:[1,0]
	v_pk_mul_f32 v[64:65], v[64:65], v[86:87] op_sel_hi:[1,0]
	v_pk_mul_f32 v[62:63], v[62:63], v[86:87] op_sel_hi:[1,0]
	v_pk_mul_f32 v[60:61], v[60:61], v[86:87] op_sel_hi:[1,0]
	s_waitcnt lgkmcnt(0)
	v_mfma_f32_16x16x32_bf16 v[64:67], v[78:81], v[74:77], v[64:67]
	ds_read_b64_tr_b16 v[78:79], v161
	ds_read_b64_tr_b16 v[80:81], v161 offset:8192
	v_pk_mul_f32 v[26:27], v[26:27], v[86:87] op_sel_hi:[1,0]
	v_pk_mul_f32 v[24:25], v[24:25], v[86:87] op_sel_hi:[1,0]
	s_waitcnt lgkmcnt(0)
	v_mfma_f32_16x16x32_bf16 v[60:63], v[78:81], v[74:77], v[60:63]
	v_mul_f32_e64 v58, v58, v86
	v_mul_f32_e64 v59, v59, v86
	v_pk_mul_f32 v[56:57], v[56:57], v[86:87] op_sel_hi:[1,0]
	v_pk_mul_f32 v[50:51], v[50:51], v[86:87] op_sel_hi:[1,0]
	v_mfma_f32_16x16x32_bf16 v[24:27], v[82:85], v[74:77], v[24:27]
	ds_read_b64_tr_b16 v[80:81], v162 offset:8192
	ds_read_b64_tr_b16 v[78:79], v162
	ds_read_b64_tr_b16 v[82:83], v163
	ds_read_b64_tr_b16 v[84:85], v163 offset:8192
	v_pk_mul_f32 v[48:49], v[48:49], v[86:87] op_sel_hi:[1,0]
	s_waitcnt lgkmcnt(2)
	v_mfma_f32_16x16x32_bf16 v[56:59], v[78:81], v[74:77], v[56:59]
	ds_read_b64_tr_b16 v[78:79], v172
	ds_read_b64_tr_b16 v[80:81], v172 offset:8192
	v_pk_mul_f32 v[54:55], v[54:55], v[86:87] op_sel_hi:[1,0]
	v_pk_mul_f32 v[52:53], v[52:53], v[86:87] op_sel_hi:[1,0]
	s_waitcnt lgkmcnt(0)
	v_mfma_f32_16x16x32_bf16 v[48:51], v[78:81], v[74:77], v[48:51]
	ds_read_b64_tr_b16 v[78:79], v173
	ds_read_b64_tr_b16 v[80:81], v173 offset:8192
	v_pk_mul_f32 v[46:47], v[46:47], v[86:87] op_sel_hi:[1,0]
	v_pk_mul_f32 v[44:45], v[44:45], v[86:87] op_sel_hi:[1,0]
	v_mfma_f32_16x16x32_bf16 v[52:55], v[82:85], v[74:77], v[52:55]
	v_mul_f32_e64 v42, v42, v86
	v_mul_f32_e64 v43, v43, v86
	v_pk_mul_f32 v[40:41], v[40:41], v[86:87] op_sel_hi:[1,0]
	v_pk_mul_f32 v[22:23], v[22:23], v[86:87] op_sel_hi:[1,0]
	s_waitcnt lgkmcnt(0)
	v_mfma_f32_16x16x32_bf16 v[44:47], v[78:81], v[74:77], v[44:47]
	ds_read_b64_tr_b16 v[80:81], v158 offset:8448
	ds_read_b64_tr_b16 v[78:79], v158 offset:256
	ds_read_b64_tr_b16 v[82:83], v159 offset:256
	ds_read_b64_tr_b16 v[84:85], v159 offset:8448
	v_pk_mul_f32 v[20:21], v[20:21], v[86:87] op_sel_hi:[1,0]
	s_waitcnt lgkmcnt(2)
	v_mfma_f32_16x16x32_bf16 v[40:43], v[78:81], v[74:77], v[40:43]
	ds_read_b64_tr_b16 v[78:79], v160 offset:256
	ds_read_b64_tr_b16 v[80:81], v160 offset:8448
	v_pk_mul_f32 v[30:31], v[30:31], v[86:87] op_sel_hi:[1,0]
	v_pk_mul_f32 v[28:29], v[28:29], v[86:87] op_sel_hi:[1,0]
	s_waitcnt lgkmcnt(0)
	v_mfma_f32_16x16x32_bf16 v[20:23], v[78:81], v[74:77], v[20:23]
	ds_read_b64_tr_b16 v[78:79], v161 offset:256
	ds_read_b64_tr_b16 v[80:81], v161 offset:8448
	v_pk_mul_f32 v[18:19], v[18:19], v[86:87] op_sel_hi:[1,0]
	v_pk_mul_f32 v[16:17], v[16:17], v[86:87] op_sel_hi:[1,0]
	v_mfma_f32_16x16x32_bf16 v[28:31], v[82:85], v[74:77], v[28:31]
	v_mul_f32_e64 v14, v14, v86
	v_mul_f32_e64 v15, v15, v86
	v_pk_mul_f32 v[12:13], v[12:13], v[86:87] op_sel_hi:[1,0]
	v_pk_mul_f32 v[6:7], v[6:7], v[86:87] op_sel_hi:[1,0]
	s_waitcnt lgkmcnt(0)
	v_mfma_f32_16x16x32_bf16 v[16:19], v[78:81], v[74:77], v[16:19]
	ds_read_b64_tr_b16 v[80:81], v162 offset:8448
	ds_read_b64_tr_b16 v[78:79], v162 offset:256
	ds_read_b64_tr_b16 v[82:83], v163 offset:256
	ds_read_b64_tr_b16 v[84:85], v163 offset:8448
	v_pk_mul_f32 v[4:5], v[4:5], v[86:87] op_sel_hi:[1,0]
	s_waitcnt lgkmcnt(2)
	v_mfma_f32_16x16x32_bf16 v[12:15], v[78:81], v[74:77], v[12:15]
	ds_read_b64_tr_b16 v[78:79], v172 offset:256
	ds_read_b64_tr_b16 v[80:81], v172 offset:8448
	v_pk_mul_f32 v[10:11], v[10:11], v[86:87] op_sel_hi:[1,0]
	v_pk_mul_f32 v[8:9], v[8:9], v[86:87] op_sel_hi:[1,0]
	s_waitcnt lgkmcnt(0)
	v_mfma_f32_16x16x32_bf16 v[4:7], v[78:81], v[74:77], v[4:7]
	ds_read_b64_tr_b16 v[78:79], v173 offset:256
	ds_read_b64_tr_b16 v[80:81], v173 offset:8448
	v_pk_mul_f32 v[2:3], v[2:3], v[86:87] op_sel_hi:[1,0]
	v_pk_mul_f32 v[0:1], v[0:1], v[86:87] op_sel_hi:[1,0]
	v_mfma_f32_16x16x32_bf16 v[8:11], v[82:85], v[74:77], v[8:11]
	s_waitcnt lgkmcnt(0)
	v_fmac_f32_e32 v72, v129, v86
	s_waitcnt lgkmcnt(0)
	v_mfma_f32_16x16x32_bf16 v[0:3], v[78:81], v[74:77], v[0:3]
	v_mov_b32_e32 v128, v73
	s_cbranch_scc0 .LBB0_136
	ds_bpermute_b32 v73, v113, v72
	v_mov_b32_e32 v124, v123
	v_mov_b32_e32 v125, v122
	v_mov_b32_e32 v126, v121
	v_mov_b32_e32 v127, v120
	s_waitcnt lgkmcnt(0)
	v_add_f32_e32 v72, v72, v73
	ds_bpermute_b32 v73, v114, v72
	s_mov_b32 s2, s25
	s_waitcnt lgkmcnt(0)
	v_add_f32_e32 v72, v72, v73
	v_div_scale_f32 v73, s[0:1], v72, v72, 1.0
	v_rcp_f32_e32 v74, v73
	s_lshl_b64 s[0:1], s[76:77], 13
	s_mov_b32 s76, s38
	v_fma_f32 v75, -v73, v74, 1.0
	v_fmac_f32_e32 v74, v75, v74
	v_div_scale_f32 v75, vcc, 1.0, v72, 1.0
	v_mul_f32_e32 v76, v75, v74
	v_fma_f32 v77, -v73, v76, v75
	v_fmac_f32_e32 v76, v77, v74
	v_fma_f32 v73, -v73, v76, v75
	v_div_fmas_f32 v73, v73, v74, v76
	v_div_fixup_f32 v72, v73, v72, 1.0
	v_pk_mul_f32 v[24:25], v[24:25], v[72:73] op_sel_hi:[1,0]
	v_pk_mul_f32 v[26:27], v[26:27], v[72:73] op_sel_hi:[1,0]
	v_lshl_add_u64 v[74:75], v[104:105], 0, s[0:1]
	v_cvt_pk_bf16_f32 v24, v24, v25
	v_cvt_pk_bf16_f32 v25, v26, v27
	global_store_dwordx2 v[74:75], v[24:25], off offset:32
	v_pk_mul_f32 v[24:25], v[64:65], v[72:73] op_sel_hi:[1,0]
	v_pk_mul_f32 v[26:27], v[66:67], v[72:73] op_sel_hi:[1,0]
	v_cvt_pk_bf16_f32 v24, v24, v25
	v_cvt_pk_bf16_f32 v25, v26, v27
	global_store_dwordx2 v[74:75], v[24:25], off offset:64
	v_pk_mul_f32 v[24:25], v[60:61], v[72:73] op_sel_hi:[1,0]
	v_pk_mul_f32 v[26:27], v[62:63], v[72:73] op_sel_hi:[1,0]
	v_cvt_pk_bf16_f32 v24, v24, v25
	v_cvt_pk_bf16_f32 v25, v26, v27
	global_store_dwordx2 v[74:75], v[24:25], off offset:96
	v_pk_mul_f32 v[24:25], v[56:57], v[72:73] op_sel_hi:[1,0]
	v_pk_mul_f32 v[26:27], v[58:59], v[72:73] op_sel_hi:[1,0]
	v_cvt_pk_bf16_f32 v24, v24, v25
	v_cvt_pk_bf16_f32 v25, v26, v27
	global_store_dwordx2 v[74:75], v[24:25], off offset:128
	v_pk_mul_f32 v[24:25], v[52:53], v[72:73] op_sel_hi:[1,0]
	v_pk_mul_f32 v[26:27], v[54:55], v[72:73] op_sel_hi:[1,0]
	v_cvt_pk_bf16_f32 v24, v24, v25
	v_cvt_pk_bf16_f32 v25, v26, v27
	global_store_dwordx2 v[74:75], v[24:25], off offset:160
	v_pk_mul_f32 v[24:25], v[48:49], v[72:73] op_sel_hi:[1,0]
	v_pk_mul_f32 v[26:27], v[50:51], v[72:73] op_sel_hi:[1,0]
	v_cvt_pk_bf16_f32 v24, v24, v25
	v_cvt_pk_bf16_f32 v25, v26, v27
	global_store_dwordx2 v[74:75], v[24:25], off offset:192
	v_pk_mul_f32 v[24:25], v[44:45], v[72:73] op_sel_hi:[1,0]
	v_pk_mul_f32 v[26:27], v[46:47], v[72:73] op_sel_hi:[1,0]
	v_cvt_pk_bf16_f32 v24, v24, v25
	v_cvt_pk_bf16_f32 v25, v26, v27
	global_store_dwordx2 v[74:75], v[24:25], off offset:224
	v_pk_mul_f32 v[24:25], v[40:41], v[72:73] op_sel_hi:[1,0]
	v_pk_mul_f32 v[26:27], v[42:43], v[72:73] op_sel_hi:[1,0]
	v_cvt_pk_bf16_f32 v24, v24, v25
	v_cvt_pk_bf16_f32 v25, v26, v27
	v_pk_mul_f32 v[68:69], v[68:69], v[72:73] op_sel_hi:[1,0]
	v_pk_mul_f32 v[70:71], v[70:71], v[72:73] op_sel_hi:[1,0]
	global_store_dwordx2 v[74:75], v[24:25], off offset:256
	v_pk_mul_f32 v[24:25], v[28:29], v[72:73] op_sel_hi:[1,0]
	v_pk_mul_f32 v[26:27], v[30:31], v[72:73] op_sel_hi:[1,0]
	v_pk_mul_f32 v[20:21], v[20:21], v[72:73] op_sel_hi:[1,0]
	v_pk_mul_f32 v[22:23], v[22:23], v[72:73] op_sel_hi:[1,0]
	v_pk_mul_f32 v[16:17], v[16:17], v[72:73] op_sel_hi:[1,0]
	v_pk_mul_f32 v[18:19], v[18:19], v[72:73] op_sel_hi:[1,0]
	v_pk_mul_f32 v[12:13], v[12:13], v[72:73] op_sel_hi:[1,0]
	v_pk_mul_f32 v[14:15], v[14:15], v[72:73] op_sel_hi:[1,0]
	v_pk_mul_f32 v[8:9], v[8:9], v[72:73] op_sel_hi:[1,0]
	v_pk_mul_f32 v[10:11], v[10:11], v[72:73] op_sel_hi:[1,0]
	v_pk_mul_f32 v[4:5], v[4:5], v[72:73] op_sel_hi:[1,0]
	v_pk_mul_f32 v[6:7], v[6:7], v[72:73] op_sel_hi:[1,0]
	v_pk_mul_f32 v[0:1], v[0:1], v[72:73] op_sel_hi:[1,0]
	v_pk_mul_f32 v[2:3], v[2:3], v[72:73] op_sel_hi:[1,0]
	v_cvt_pk_bf16_f32 v68, v68, v69
	v_cvt_pk_bf16_f32 v69, v70, v71
	v_cvt_pk_bf16_f32 v24, v24, v25
	v_cvt_pk_bf16_f32 v25, v26, v27
	v_cvt_pk_bf16_f32 v20, v20, v21
	v_cvt_pk_bf16_f32 v21, v22, v23
	v_cvt_pk_bf16_f32 v16, v16, v17
	v_cvt_pk_bf16_f32 v17, v18, v19
	v_cvt_pk_bf16_f32 v12, v12, v13
	v_cvt_pk_bf16_f32 v13, v14, v15
	v_cvt_pk_bf16_f32 v8, v8, v9
	v_cvt_pk_bf16_f32 v9, v10, v11
	v_cvt_pk_bf16_f32 v4, v4, v5
	v_cvt_pk_bf16_f32 v5, v6, v7
	v_cvt_pk_bf16_f32 v0, v0, v1
	v_cvt_pk_bf16_f32 v1, v2, v3
	s_and_b64 vcc, exec, s[40:41]
	global_store_dwordx2 v[74:75], v[68:69], off
	global_store_dwordx2 v[74:75], v[24:25], off offset:288
	global_store_dwordx2 v[74:75], v[20:21], off offset:320
	global_store_dwordx2 v[74:75], v[16:17], off offset:352
	global_store_dwordx2 v[74:75], v[12:13], off offset:384
	global_store_dwordx2 v[74:75], v[8:9], off offset:416
	global_store_dwordx2 v[74:75], v[4:5], off offset:448
	global_store_dwordx2 v[74:75], v[0:1], off offset:480
	s_cbranch_vccz .LBB0_128

	.amdhsa_kernel _Z9trunk_fwd6Params
		.amdhsa_group_segment_fixed_size 0
		.amdhsa_private_segment_fixed_size 0
		.amdhsa_kernarg_size 424
		.amdhsa_user_sgpr_count 2
		.amdhsa_user_sgpr_dispatch_ptr 0
		.amdhsa_user_sgpr_queue_ptr 0
		.amdhsa_user_sgpr_kernarg_segment_ptr 1
		.amdhsa_user_sgpr_dispatch_id 0
		.amdhsa_user_sgpr_kernarg_preload_length 0
		.amdhsa_user_sgpr_kernarg_preload_offset 0
		.amdhsa_user_sgpr_private_segment_size 0
		.amdhsa_uses_dynamic_stack 0
		.amdhsa_enable_private_segment 0
		.amdhsa_system_sgpr_workgroup_id_x 1
		.amdhsa_system_sgpr_workgroup_id_y 0
		.amdhsa_system_sgpr_workgroup_id_z 0
		.amdhsa_system_sgpr_workgroup_info 0
		.amdhsa_system_vgpr_workitem_id 2
		.amdhsa_next_free_vgpr 256
		.amdhsa_next_free_sgpr 102
		.amdhsa_accum_offset 256
		.amdhsa_reserve_vcc 1
		.amdhsa_float_round_mode_32 0
		.amdhsa_float_round_mode_16_64 0
		.amdhsa_float_denorm_mode_32 3
		.amdhsa_float_denorm_mode_16_64 3
		.amdhsa_dx10_clamp 1
		.amdhsa_ieee_mode 1
		.amdhsa_fp16_overflow 0
		.amdhsa_tg_split 0
		.amdhsa_exception_fp_ieee_invalid_op 0
		.amdhsa_exception_fp_denorm_src 0
		.amdhsa_exception_fp_ieee_div_zero 0
		.amdhsa_exception_fp_ieee_overflow 0
		.amdhsa_exception_fp_ieee_underflow 0
		.amdhsa_exception_fp_ieee_inexact 0
		.amdhsa_exception_int_div_zero 0
	.end_amdhsa_kernel

amdhsa.kernels:
  - .agpr_count:     0
    .args:
      - .offset:         0
        .size:           168
        .value_kind:     by_value
      - .offset:         168
        .size:           4
        .value_kind:     hidden_block_count_x
      - .offset:         172
        .size:           4
        .value_kind:     hidden_block_count_y
      - .offset:         176
        .size:           4
        .value_kind:     hidden_block_count_z
      - .offset:         180
        .size:           2
        .value_kind:     hidden_group_size_x
      - .offset:         182
        .size:           2
        .value_kind:     hidden_group_size_y
      - .offset:         184
        .size:           2
        .value_kind:     hidden_group_size_z
      - .offset:         186
        .size:           2
        .value_kind:     hidden_remainder_x
      - .offset:         188
        .size:           2
        .value_kind:     hidden_remainder_y
      - .offset:         190
        .size:           2
        .value_kind:     hidden_remainder_z
      - .offset:         208
        .size:           8
        .value_kind:     hidden_global_offset_x
      - .offset:         216
        .size:           8
        .value_kind:     hidden_global_offset_y
      - .offset:         224
        .size:           8
        .value_kind:     hidden_global_offset_z
      - .offset:         232
        .size:           2
        .value_kind:     hidden_grid_dims
      - .offset:         256
        .size:           8
        .value_kind:     hidden_multigrid_sync_arg
      - .offset:         288
        .size:           4
        .value_kind:     hidden_dynamic_lds_size
    .group_segment_fixed_size: 0
    .kernarg_segment_align: 8
    .kernarg_segment_size: 424
    .language:       OpenCL C
    .language_version:
      - 2
      - 0
    .max_flat_workgroup_size: 512
    .name:           _Z9trunk_fwd6Params
    .private_segment_fixed_size: 0
    .sgpr_count:     108
    .sgpr_spill_count: 368
    .symbol:         _Z9trunk_fwd6Params.kd
    .uniform_work_group_size: 1
    .uses_dynamic_stack: false
    .vgpr_count:     256
    .vgpr_spill_count: 0
    .wavefront_size: 64
